# LDS-DMA staging with the four DMAs spread one per MFMA gap after the barrier (instead of a burst at the barrier)
# speedup vs baseline: 1.0834x; 1.0131x over previous
; #define SBAR() __builtin_amdgcn_sched_barrier(0)
; #define PVE_M(OD, PA, L, H, IDX) do { OD = __builtin_amdgcn_mfma_f32_32x32x16_bf16(PA, PKV(L, H), OD, 0, 0, 0); SBAR(); p[IDX] = __builtin_amdgcn_exp2f(p[IDX]); asm volatile("" : "+v"(p)); SBAR(); } while (0)
; __device__ __forceinline__ void pv_exp(f32x16* o, int vb, bf16x8 pa0, bf16x8 pa1, bf16x8 pa2, bf16x8 pa3, f32x16& p, VF8& fa) {
;   VF8 fb;
;   asm volatile("s_waitcnt lgkmcnt(0)" ::: "memory"); SBAR();
;   PVE_M(o[0], pa0, fa.l0, fa.h0, 0); PVE_M(o[0], pa1, fa.l1, fa.h1, 1); vf8_read<1>(fb, vb); SBAR(); PVE_M(o[0], pa2, fa.l2, fa.h2, 2); PVE_M(o[0], pa3, fa.l3, fa.h3, 3);
;   asm volatile("s_waitcnt lgkmcnt(0)" ::: "memory"); SBAR();
;   PVE_M(o[1], pa0, fb.l0, fb.h0, 4); PVE_M(o[1], pa1, fb.l1, fb.h1, 5); vf8_read<2>(fa, vb); SBAR(); PVE_M(o[1], pa2, fb.l2, fb.h2, 6); PVE_M(o[1], pa3, fb.l3, fb.h3, 7);
;   asm volatile("s_waitcnt lgkmcnt(0)" ::: "memory"); SBAR();
;   PVE_M(o[2], pa0, fa.l0, fa.h0, 8); PVE_M(o[2], pa1, fa.l1, fa.h1, 9); vf8_read<3>(fb, vb); SBAR(); PVE_M(o[2], pa2, fa.l2, fa.h2, 10); PVE_M(o[2], pa3, fa.l3, fa.h3, 11);
;   asm volatile("s_waitcnt lgkmcnt(0)" ::: "memory"); SBAR();
;   PVE_M(o[3], pa0, fb.l0, fb.h0, 12); PVE_M(o[3], pa1, fb.l1, fb.h1, 13); PVE_M(o[3], pa2, fb.l2, fb.h2, 14); PVE_M(o[3], pa3, fb.l3, fb.h3, 15);
; }
.LBB0_457:
	s_waitcnt vmcnt(0)
	s_barrier
	s_waitcnt lgkmcnt(0)
	v_mfma_f32_32x32x16_bf16 v[50:65], v[196:199], v[94:97], v[50:65]
	v_exp_f32_e32 v132, v132
	v_mfma_f32_32x32x16_bf16 v[50:65], v[204:207], v[90:93], v[50:65]
	v_exp_f32_e32 v133, v133
	ds_read_b64_tr_b16 v[90:91], v0 offset:0x200
	ds_read_b64_tr_b16 v[92:93], v0 offset:0xa00
	ds_read_b64_tr_b16 v[94:95], v0 offset:0x1200
	ds_read_b64_tr_b16 v[96:97], v0 offset:0x1a00
	ds_read_b64_tr_b16 v[114:115], v0 offset:0x2200
	ds_read_b64_tr_b16 v[116:117], v0 offset:0x2a00
	ds_read_b64_tr_b16 v[118:119], v0 offset:0x3200
	ds_read_b64_tr_b16 v[120:121], v0 offset:0x3a00
	v_mfma_f32_32x32x16_bf16 v[50:65], v[200:203], v[86:89], v[50:65]
	v_exp_f32_e32 v134, v134
	s_add_i32 s79, s98, s100
	s_add_i32 m0, s79, 0x4000
	s_add_i32 s79, s79, 0x6000
	global_load_lds_dwordx4 v[180:181], off
	v_mfma_f32_32x32x16_bf16 v[50:65], v[208:211], v[82:85], v[50:65]
	v_exp_f32_e32 v135, v135
	s_mov_b32 m0, s79
	s_add_i32 s79, s98, s101
	global_load_lds_dwordx4 v[182:183], off
	s_waitcnt lgkmcnt(0)
	v_mfma_f32_32x32x16_bf16 v[34:49], v[196:199], v[90:93], v[34:49]
	v_exp_f32_e32 v136, v136
	s_mov_b32 m0, s79
	s_add_i32 s79, s79, 0x380
	global_load_lds_dwordx4 v[214:215], off
	v_mfma_f32_32x32x16_bf16 v[34:49], v[204:207], v[94:97], v[34:49]
	v_exp_f32_e32 v137, v137
	ds_read_b64_tr_b16 v[82:83], v0 offset:0x400
	ds_read_b64_tr_b16 v[84:85], v0 offset:0xc00
	ds_read_b64_tr_b16 v[86:87], v0 offset:0x1400
	ds_read_b64_tr_b16 v[88:89], v0 offset:0x1c00
	ds_read_b64_tr_b16 v[90:91], v0 offset:0x2400
	ds_read_b64_tr_b16 v[92:93], v0 offset:0x2c00
	ds_read_b64_tr_b16 v[94:95], v0 offset:0x3400
	ds_read_b64_tr_b16 v[96:97], v0 offset:0x3c00
	v_mfma_f32_32x32x16_bf16 v[34:49], v[200:203], v[114:117], v[34:49]
	v_exp_f32_e32 v138, v138
	s_mov_b32 m0, s79
	s_nop 0
	global_load_lds_dwordx4 v[214:215], off offset:128
	v_lshl_add_u64 v[180:181], v[180:181], 0, s[76:77]
	v_lshl_add_u64 v[182:183], v[182:183], 0, s[76:77]
	v_lshl_add_u64 v[214:215], v[214:215], 0, s[76:77]
	v_mfma_f32_32x32x16_bf16 v[34:49], v[208:211], v[118:121], v[34:49]
	v_exp_f32_e32 v139, v139
	s_waitcnt lgkmcnt(0)
	v_mfma_f32_32x32x16_bf16 v[18:33], v[196:199], v[82:85], v[18:33]
	v_exp_f32_e32 v140, v140
	v_mfma_f32_32x32x16_bf16 v[18:33], v[204:207], v[86:89], v[18:33]
	v_exp_f32_e32 v141, v141
	ds_read_b64_tr_b16 v[82:83], v0 offset:0x600
	ds_read_b64_tr_b16 v[84:85], v0 offset:0xe00
	ds_read_b64_tr_b16 v[86:87], v0 offset:0x1600
	ds_read_b64_tr_b16 v[88:89], v0 offset:0x1e00
	ds_read_b64_tr_b16 v[114:115], v0 offset:0x2600
	ds_read_b64_tr_b16 v[116:117], v0 offset:0x2e00
	ds_read_b64_tr_b16 v[118:119], v0 offset:0x3600
	ds_read_b64_tr_b16 v[120:121], v0 offset:0x3e00
	v_mfma_f32_32x32x16_bf16 v[18:33], v[200:203], v[90:93], v[18:33]
	v_exp_f32_e32 v142, v142
	v_mfma_f32_32x32x16_bf16 v[18:33], v[208:211], v[94:97], v[18:33]
	v_exp_f32_e32 v143, v143
	s_waitcnt lgkmcnt(0)
	v_mfma_f32_32x32x16_bf16 v[2:17], v[196:199], v[82:85], v[2:17]
	v_exp_f32_e32 v144, v144
	v_mfma_f32_32x32x16_bf16 v[2:17], v[204:207], v[86:89], v[2:17]
	v_exp_f32_e32 v145, v145
	v_mfma_f32_32x32x16_bf16 v[2:17], v[200:203], v[114:117], v[2:17]
	v_exp_f32_e32 v146, v146
	v_mfma_f32_32x32x16_bf16 v[2:17], v[208:211], v[118:121], v[2:17]
	v_exp_f32_e32 v147, v147
	v_cmp_gt_f32_e32 vcc, 1.0, v130
	s_cbranch_vccz .LBB0_461
	s_and_saveexec_b64 s[36:37], s[6:7]
	ds_write_b32 v220, v130 offset:128
	s_or_b64 exec, exec, s[36:37]
	s_waitcnt lgkmcnt(0)
	v_add_u32_e32 v94, v213, v212
	ds_read_b128 v[82:85], v94 offset:224
	ds_read_b128 v[86:89], v94 offset:192
	ds_read_b128 v[90:93], v94 offset:160
	ds_read_b128 v[94:97], v94 offset:128
	s_waitcnt lgkmcnt(3)
	v_pk_mul_f32 v[62:63], v[62:63], v[82:83]
	s_waitcnt lgkmcnt(2)
	v_pk_mul_f32 v[58:59], v[58:59], v[86:87]
	s_waitcnt lgkmcnt(1)
	v_pk_mul_f32 v[54:55], v[54:55], v[90:91]
	v_pk_mul_f32 v[64:65], v[64:65], v[84:85]
	v_pk_mul_f32 v[60:61], v[60:61], v[88:89]
	v_pk_mul_f32 v[56:57], v[56:57], v[92:93]
	s_waitcnt lgkmcnt(0)
	v_pk_mul_f32 v[52:53], v[52:53], v[96:97]
	v_pk_mul_f32 v[50:51], v[50:51], v[94:95]
	v_pk_mul_f32 v[46:47], v[46:47], v[82:83]
	v_pk_mul_f32 v[42:43], v[42:43], v[86:87]
	v_pk_mul_f32 v[38:39], v[38:39], v[90:91]
	v_pk_mul_f32 v[48:49], v[48:49], v[84:85]
	v_pk_mul_f32 v[44:45], v[44:45], v[88:89]
	v_pk_mul_f32 v[40:41], v[40:41], v[92:93]
	v_pk_mul_f32 v[36:37], v[36:37], v[96:97]
	v_pk_mul_f32 v[34:35], v[34:35], v[94:95]
	v_pk_mul_f32 v[30:31], v[30:31], v[82:83]
	v_pk_mul_f32 v[26:27], v[26:27], v[86:87]
	v_pk_mul_f32 v[22:23], v[22:23], v[90:91]
	v_pk_mul_f32 v[32:33], v[32:33], v[84:85]
	v_pk_mul_f32 v[28:29], v[28:29], v[88:89]
	v_pk_mul_f32 v[24:25], v[24:25], v[92:93]
	v_pk_mul_f32 v[20:21], v[20:21], v[96:97]
	v_pk_mul_f32 v[18:19], v[18:19], v[94:95]
	v_pk_mul_f32 v[14:15], v[14:15], v[82:83]
	v_pk_mul_f32 v[10:11], v[10:11], v[86:87]
	v_pk_mul_f32 v[6:7], v[6:7], v[90:91]
	v_pk_mul_f32 v[16:17], v[16:17], v[84:85]
	v_pk_mul_f32 v[12:13], v[12:13], v[88:89]
	v_pk_mul_f32 v[8:9], v[8:9], v[92:93]
	v_pk_mul_f32 v[4:5], v[4:5], v[96:97]
	v_pk_mul_f32 v[2:3], v[2:3], v[94:95]

; #define SBAR() __builtin_amdgcn_sched_barrier(0)
; #define PVE_M(OD, PA, L, H, IDX) do { OD = __builtin_amdgcn_mfma_f32_32x32x16_bf16(PA, PKV(L, H), OD, 0, 0, 0); SBAR(); p[IDX] = __builtin_amdgcn_exp2f(p[IDX]); asm volatile("" : "+v"(p)); SBAR(); } while (0)
; __device__ __forceinline__ void pv_exp(f32x16* o, int vb, bf16x8 pa0, bf16x8 pa1, bf16x8 pa2, bf16x8 pa3, f32x16& p, VF8& fa) {
;   VF8 fb;
;   asm volatile("s_waitcnt lgkmcnt(0)" ::: "memory"); SBAR();
;   PVE_M(o[0], pa0, fa.l0, fa.h0, 0); PVE_M(o[0], pa1, fa.l1, fa.h1, 1); vf8_read<1>(fb, vb); SBAR(); PVE_M(o[0], pa2, fa.l2, fa.h2, 2); PVE_M(o[0], pa3, fa.l3, fa.h3, 3);
;   asm volatile("s_waitcnt lgkmcnt(0)" ::: "memory"); SBAR();
;   PVE_M(o[1], pa0, fb.l0, fb.h0, 4); PVE_M(o[1], pa1, fb.l1, fb.h1, 5); vf8_read<2>(fa, vb); SBAR(); PVE_M(o[1], pa2, fb.l2, fb.h2, 6); PVE_M(o[1], pa3, fb.l3, fb.h3, 7);
;   asm volatile("s_waitcnt lgkmcnt(0)" ::: "memory"); SBAR();
;   PVE_M(o[2], pa0, fa.l0, fa.h0, 8); PVE_M(o[2], pa1, fa.l1, fa.h1, 9); vf8_read<3>(fb, vb); SBAR(); PVE_M(o[2], pa2, fa.l2, fa.h2, 10); PVE_M(o[2], pa3, fa.l3, fa.h3, 11);
;   asm volatile("s_waitcnt lgkmcnt(0)" ::: "memory"); SBAR();
;   PVE_M(o[3], pa0, fb.l0, fb.h0, 12); PVE_M(o[3], pa1, fb.l1, fb.h1, 13); PVE_M(o[3], pa2, fb.l2, fb.h2, 14); PVE_M(o[3], pa3, fb.l3, fb.h3, 15);
; }
.LBB0_463:
	s_waitcnt vmcnt(0)
	s_barrier
	s_waitcnt lgkmcnt(0)
	v_mfma_f32_32x32x16_bf16 v[50:65], v[132:135], v[144:147], v[50:65]
	v_exp_f32_e32 v114, v114
	v_mfma_f32_32x32x16_bf16 v[50:65], v[136:139], v[106:109], v[50:65]
	v_exp_f32_e32 v115, v115
	ds_read_b64_tr_b16 v[106:107], v203 offset:0x200
	ds_read_b64_tr_b16 v[108:109], v203 offset:0xa00
	ds_read_b64_tr_b16 v[144:145], v203 offset:0x1200
	ds_read_b64_tr_b16 v[146:147], v203 offset:0x1a00
	ds_read_b64_tr_b16 v[204:205], v203 offset:0x2200
	ds_read_b64_tr_b16 v[206:207], v203 offset:0x2a00
	ds_read_b64_tr_b16 v[208:209], v203 offset:0x3200
	ds_read_b64_tr_b16 v[210:211], v203 offset:0x3a00
	v_mfma_f32_32x32x16_bf16 v[50:65], v[196:199], v[102:105], v[50:65]
	v_exp_f32_e32 v116, v116
	s_add_i32 s79, s97, s100
	s_add_i32 m0, s79, 0x4000
	s_add_i32 s79, s79, 0x6000
	global_load_lds_dwordx4 v[180:181], off
	v_mfma_f32_32x32x16_bf16 v[50:65], v[140:143], v[98:101], v[50:65]
	v_exp_f32_e32 v117, v117
	s_mov_b32 m0, s79
	s_add_i32 s79, s97, s101
	global_load_lds_dwordx4 v[182:183], off
	s_waitcnt lgkmcnt(0)
	v_mfma_f32_32x32x16_bf16 v[34:49], v[132:135], v[106:109], v[34:49]
	v_exp_f32_e32 v118, v118
	s_mov_b32 m0, s79
	s_add_i32 s79, s79, 0x380
	global_load_lds_dwordx4 v[214:215], off
	v_mfma_f32_32x32x16_bf16 v[34:49], v[136:139], v[144:147], v[34:49]
	v_exp_f32_e32 v119, v119
	ds_read_b64_tr_b16 v[98:99], v203 offset:0x400
	ds_read_b64_tr_b16 v[100:101], v203 offset:0xc00
	ds_read_b64_tr_b16 v[102:103], v203 offset:0x1400
	ds_read_b64_tr_b16 v[104:105], v203 offset:0x1c00
	ds_read_b64_tr_b16 v[106:107], v203 offset:0x2400
	ds_read_b64_tr_b16 v[108:109], v203 offset:0x2c00
	ds_read_b64_tr_b16 v[144:145], v203 offset:0x3400
	ds_read_b64_tr_b16 v[146:147], v203 offset:0x3c00
	v_mfma_f32_32x32x16_bf16 v[34:49], v[196:199], v[204:207], v[34:49]
	v_exp_f32_e32 v120, v120
	s_mov_b32 m0, s79
	s_nop 0
	global_load_lds_dwordx4 v[214:215], off offset:128
	v_lshl_add_u64 v[180:181], v[180:181], 0, s[76:77]
	v_lshl_add_u64 v[182:183], v[182:183], 0, s[76:77]
	v_lshl_add_u64 v[214:215], v[214:215], 0, s[76:77]
	v_mfma_f32_32x32x16_bf16 v[34:49], v[140:143], v[208:211], v[34:49]
	v_exp_f32_e32 v121, v121
	s_waitcnt lgkmcnt(0)
	v_mfma_f32_32x32x16_bf16 v[18:33], v[132:135], v[98:101], v[18:33]
	v_exp_f32_e32 v122, v122
	v_mfma_f32_32x32x16_bf16 v[18:33], v[136:139], v[102:105], v[18:33]
	v_exp_f32_e32 v123, v123
	ds_read_b64_tr_b16 v[98:99], v203 offset:0x600
	ds_read_b64_tr_b16 v[100:101], v203 offset:0xe00
	ds_read_b64_tr_b16 v[102:103], v203 offset:0x1600
	ds_read_b64_tr_b16 v[104:105], v203 offset:0x1e00
	ds_read_b64_tr_b16 v[204:205], v203 offset:0x2600
	ds_read_b64_tr_b16 v[206:207], v203 offset:0x2e00
	ds_read_b64_tr_b16 v[208:209], v203 offset:0x3600
	ds_read_b64_tr_b16 v[210:211], v203 offset:0x3e00
	v_mfma_f32_32x32x16_bf16 v[18:33], v[196:199], v[106:109], v[18:33]
	v_exp_f32_e32 v124, v124
	v_mfma_f32_32x32x16_bf16 v[18:33], v[140:143], v[144:147], v[18:33]
	v_exp_f32_e32 v125, v125
	s_waitcnt lgkmcnt(0)
	v_mfma_f32_32x32x16_bf16 v[2:17], v[132:135], v[98:101], v[2:17]
	v_exp_f32_e32 v126, v126
	v_mfma_f32_32x32x16_bf16 v[2:17], v[136:139], v[102:105], v[2:17]
	v_exp_f32_e32 v127, v127
	v_mfma_f32_32x32x16_bf16 v[2:17], v[196:199], v[204:207], v[2:17]
	v_exp_f32_e32 v128, v128
	v_mfma_f32_32x32x16_bf16 v[2:17], v[140:143], v[208:211], v[2:17]
	v_exp_f32_e32 v129, v129
	v_cmp_gt_f32_e32 vcc, 1.0, v200
	s_cbranch_vccz .LBB0_467
	s_and_saveexec_b64 s[36:37], s[6:7]
	ds_write_b32 v220, v200 offset:128
	s_or_b64 exec, exec, s[36:37]
	s_waitcnt lgkmcnt(0)
	v_add_u32_e32 v110, v213, v212
	ds_read_b128 v[98:101], v110 offset:224
	ds_read_b128 v[102:105], v110 offset:192
	ds_read_b128 v[106:109], v110 offset:160
	ds_read_b128 v[132:135], v110 offset:128
	s_waitcnt lgkmcnt(3)
	v_pk_mul_f32 v[62:63], v[62:63], v[98:99]
	s_waitcnt lgkmcnt(2)
	v_pk_mul_f32 v[58:59], v[58:59], v[102:103]
	s_waitcnt lgkmcnt(1)
	v_pk_mul_f32 v[54:55], v[54:55], v[106:107]
	v_pk_mul_f32 v[64:65], v[64:65], v[100:101]
	v_pk_mul_f32 v[60:61], v[60:61], v[104:105]
	v_pk_mul_f32 v[56:57], v[56:57], v[108:109]
	s_waitcnt lgkmcnt(0)
	v_pk_mul_f32 v[52:53], v[52:53], v[134:135]
	v_pk_mul_f32 v[50:51], v[50:51], v[132:133]
	v_pk_mul_f32 v[46:47], v[46:47], v[98:99]
	v_pk_mul_f32 v[42:43], v[42:43], v[102:103]
	v_pk_mul_f32 v[38:39], v[38:39], v[106:107]
	v_pk_mul_f32 v[48:49], v[48:49], v[100:101]
	v_pk_mul_f32 v[44:45], v[44:45], v[104:105]
	v_pk_mul_f32 v[40:41], v[40:41], v[108:109]
	v_pk_mul_f32 v[36:37], v[36:37], v[134:135]
	v_pk_mul_f32 v[34:35], v[34:35], v[132:133]
	v_pk_mul_f32 v[30:31], v[30:31], v[98:99]
	v_pk_mul_f32 v[26:27], v[26:27], v[102:103]
	v_pk_mul_f32 v[22:23], v[22:23], v[106:107]
	v_pk_mul_f32 v[32:33], v[32:33], v[100:101]
	v_pk_mul_f32 v[28:29], v[28:29], v[104:105]
	v_pk_mul_f32 v[24:25], v[24:25], v[108:109]
	v_pk_mul_f32 v[20:21], v[20:21], v[134:135]
	v_pk_mul_f32 v[18:19], v[18:19], v[132:133]
	v_pk_mul_f32 v[14:15], v[14:15], v[98:99]
	v_pk_mul_f32 v[10:11], v[10:11], v[102:103]
	v_pk_mul_f32 v[6:7], v[6:7], v[106:107]
	v_pk_mul_f32 v[16:17], v[16:17], v[100:101]
	v_pk_mul_f32 v[12:13], v[12:13], v[104:105]
	v_pk_mul_f32 v[8:9], v[8:9], v[108:109]
	v_pk_mul_f32 v[4:5], v[4:5], v[134:135]
	v_pk_mul_f32 v[2:3], v[2:3], v[132:133]

; #define SBAR() __builtin_amdgcn_sched_barrier(0)
; __device__ __forceinline__ unsigned cvtpk(float lo, float hi) { unsigned r; asm volatile("v_cvt_pk_bf16_f32 %0, %1, %2" : "=v"(r) : "v"(lo), "v"(hi)); return r; }
; #define SLOAD(k0) do { sr_.vs0 = *(const bf16x8*)(&Vh[(long)((k0) + sr) * LDK + sc]); sr_.vs1 = *(const bf16x8*)(&Vh[(long)((k0) + 32 + sr) * LDK + sc]); \
;     sr_.ks0 = *(const bf16x8*)(&Kh[(long)((k0) + sr) * LDK + sc]); sr_.ks1 = *(const bf16x8*)(&Kh[(long)((k0) + 32 + sr) * LDK + sc]); } while (0)
; __device__ __forceinline__ void qkt_fin(f32x16& n0, f32x16& n1, const bf16_t* Ks, const bf16x8* qr, const f32x16& negm, int r32, int hi, ...
;   float psa = 0.f, psb = 0.f; u32x4 wa, wb, wc, wd;
;     ...
; #pragma unroll
;   for (int d0 = 0; d0 < 8; ++d0) { int cb = (d0 * 16 + hi * 8) * 2;
;     bf16x8 b0 = *reinterpret_cast<const bf16x8*>((const char*)Ks + KSWZ(r32, cb));
;     bf16x8 b1 = *reinterpret_cast<const bf16x8*>((const char*)Ks + KSWZ(32 + r32, cb));
;     SBAR(); if (d0 == 0) n0 = __builtin_amdgcn_mfma_f32_32x32x16_bf16(b0, qr[0], negm, 0, 0, 0); else n0 = __builtin_amdgcn_mfma_f32_32x32x16_bf16(b0, qr[d0], n0, 0, 0, 0);
;     SBAR(); QF_CHUNK(2 * d0); SBAR();
;     if (d0 == 0) n1 = __builtin_amdgcn_mfma_f32_32x32x16_bf16(b1, qr[0], negm, 0, 0, 0); else n1 = __builtin_amdgcn_mfma_f32_32x32x16_bf16(b1, qr[d0], n1, 0, 0, 0);
;     SBAR(); QF_CHUNK(2 * d0 + 1); SBAR();
;     if (d0 == 7) { vf8_read<0>(vf0, vbv); SBAR(); } }
;     ...
;   psb += P1[15]; wd[3] = cvtpk(P1[14], P1[15]);
;   l_reg = l_reg * alpha + (psa + psb);
;   pa0 = *reinterpret_cast<bf16x8*>(&wa); pa1 = *reinterpret_cast<bf16x8*>(&wb); pa2 = *reinterpret_cast<bf16x8*>(&wc); pa3 = *reinterpret_cast<bf16x8*>(&wd);
; }
; __device__ __forceinline__ void attn_item(const bf16_t* __restrict__ Qb, const bf16_t* __restrict__ Kh, const bf16_t* __restrict__ Vh, const bf16_t* __restrict__ Zb, ...
;     ...
;     SBAR(); SLOAD((j + 1) * KVBLK); SBAR();
;     qkt_fin(pB0, pB1, (const bf16_t*)(lds + s_cur + KOFF), qr, negm, r32, hi, pA0, pA1, alA, l_reg, pa0, pa1, pa2, pa3, vfa, vb0 + s_prev); SBAR();
.Lh2_453:
	s_add_i32 s97, s96, 0xffff8000
	s_xor_b32 s98, s96, 0x10000
	s_add_i32 s99, s96, 0x8000
	s_and_b32 s99, s99, 0x18000
	v_add_u32_e32 v196, s96, v236
	ds_read_b128 v[98:101], v196 offset:16384
	ds_read_b128 v[196:199], v196 offset:24576
	v_add_u32_e32 v252, s96, v237
	ds_read_b128 v[248:251], v252 offset:16384
	ds_read_b128 v[252:255], v252 offset:24576
	v_add_u32_e32 v0, s97, v235
	s_waitcnt lgkmcnt(3)
	v_mfma_f32_32x32x16_bf16 v[132:147], v[98:101], v[152:155], v[66:81]
	v_exp_f32_e32 v82, v82
	s_waitcnt lgkmcnt(2)
	v_mfma_f32_32x32x16_bf16 v[98:113], v[196:199], v[152:155], v[66:81]
	v_exp_f32_e32 v83, v83
	v_add_f32_e32 v245, v115, v114
	v_cvt_pk_bf16_f32 v196, v114, v115
	v_add_u32_e32 v206, s96, v238
	ds_read_b128 v[202:205], v206 offset:16384
	ds_read_b128 v[206:209], v206 offset:24576
	s_add_i32 s79, s99, s100
	s_add_i32 m0, s79, 0x4000
	s_add_i32 s79, s79, 0x6000
	global_load_lds_dwordx4 v[180:181], off
	s_waitcnt lgkmcnt(3)
	v_mfma_f32_32x32x16_bf16 v[132:147], v[248:251], v[160:163], v[132:147]
	v_exp_f32_e32 v84, v84
	v_add_f32_e32 v245, v116, v245
	v_add_f32_e32 v246, v82, v83
	s_waitcnt lgkmcnt(2)
	v_mfma_f32_32x32x16_bf16 v[98:113], v[252:255], v[160:163], v[98:113]
	v_exp_f32_e32 v85, v85
	v_add_f32_e32 v245, v117, v245
	v_add_f32_e32 v246, v246, v84
	v_cvt_pk_bf16_f32 v197, v116, v117
	v_cvt_pk_bf16_f32 v200, v82, v83
	v_add_u32_e32 v252, s96, v239
	ds_read_b128 v[248:251], v252 offset:16384
	ds_read_b128 v[252:255], v252 offset:24576
	s_mov_b32 m0, s79
	s_add_i32 s79, s99, s101
	global_load_lds_dwordx4 v[182:183], off
	s_waitcnt lgkmcnt(3)
	v_mfma_f32_32x32x16_bf16 v[132:147], v[202:205], v[148:151], v[132:147]
	v_exp_f32_e32 v86, v86
	v_add_f32_e32 v245, v118, v245
	v_add_f32_e32 v246, v246, v85
	s_waitcnt lgkmcnt(2)
	v_mfma_f32_32x32x16_bf16 v[98:113], v[206:209], v[148:151], v[98:113]
	v_exp_f32_e32 v87, v87
	v_add_f32_e32 v245, v119, v245
	v_add_f32_e32 v246, v246, v86
	v_cvt_pk_bf16_f32 v198, v118, v119
	v_cvt_pk_bf16_f32 v201, v84, v85
	v_add_u32_e32 v208, s96, v240
	ds_read_b128 v[204:207], v208 offset:16384
	ds_read_b128 v[208:211], v208 offset:24576
	s_mov_b32 m0, s79
	s_add_i32 s79, s79, 0x380
	global_load_lds_dwordx4 v[214:215], off
	s_waitcnt lgkmcnt(3)
	v_mfma_f32_32x32x16_bf16 v[132:147], v[248:251], v[156:159], v[132:147]
	v_exp_f32_e32 v88, v88
	v_add_f32_e32 v245, v120, v245
	v_add_f32_e32 v246, v246, v87
	s_waitcnt lgkmcnt(2)
	v_mfma_f32_32x32x16_bf16 v[98:113], v[252:255], v[156:159], v[98:113]
	v_exp_f32_e32 v89, v89
	v_add_f32_e32 v245, v121, v245
	v_add_f32_e32 v246, v246, v88
	v_cvt_pk_bf16_f32 v199, v120, v121
	v_cvt_pk_bf16_f32 v202, v86, v87
	v_add_u32_e32 v252, s96, v241
	ds_read_b128 v[248:251], v252 offset:16384
	ds_read_b128 v[252:255], v252 offset:24576
	s_mov_b32 m0, s79
	s_nop 0
	global_load_lds_dwordx4 v[214:215], off offset:128
	v_lshl_add_u64 v[180:181], v[180:181], 0, s[76:77]
	v_lshl_add_u64 v[182:183], v[182:183], 0, s[76:77]
	v_lshl_add_u64 v[214:215], v[214:215], 0, s[76:77]
	s_waitcnt lgkmcnt(3)
	v_mfma_f32_32x32x16_bf16 v[132:147], v[204:207], v[168:171], v[132:147]
	v_exp_f32_e32 v90, v90
	v_add_f32_e32 v245, v122, v245
	v_add_f32_e32 v246, v246, v89
	s_waitcnt lgkmcnt(2)
	v_mfma_f32_32x32x16_bf16 v[98:113], v[208:211], v[168:171], v[98:113]
	v_exp_f32_e32 v91, v91
	v_add_f32_e32 v245, v123, v245
	v_add_f32_e32 v246, v246, v90
	v_cvt_pk_bf16_f32 v204, v122, v123
	v_cvt_pk_bf16_f32 v203, v88, v89
	v_add_u32_e32 v118, s96, v242
	ds_read_b128 v[114:117], v118 offset:16384
	ds_read_b128 v[118:121], v118 offset:24576
	s_waitcnt lgkmcnt(3)
	v_mfma_f32_32x32x16_bf16 v[132:147], v[248:251], v[176:179], v[132:147]
	v_exp_f32_e32 v92, v92
	v_add_f32_e32 v245, v124, v245
	v_add_f32_e32 v246, v246, v91
	s_waitcnt lgkmcnt(2)
	v_mfma_f32_32x32x16_bf16 v[98:113], v[252:255], v[176:179], v[98:113]
	v_exp_f32_e32 v93, v93
	v_add_f32_e32 v245, v125, v245
	v_add_f32_e32 v246, v246, v92
	v_cvt_pk_bf16_f32 v205, v124, v125
	v_cvt_pk_bf16_f32 v208, v90, v91
	v_add_u32_e32 v252, s96, v243
	ds_read_b128 v[248:251], v252 offset:16384
	ds_read_b128 v[252:255], v252 offset:24576
	s_waitcnt lgkmcnt(3)
	v_mfma_f32_32x32x16_bf16 v[132:147], v[114:117], v[164:167], v[132:147]
	v_exp_f32_e32 v94, v94
	v_add_f32_e32 v245, v126, v245
	v_add_f32_e32 v246, v246, v93
	s_waitcnt lgkmcnt(2)
	v_mfma_f32_32x32x16_bf16 v[98:113], v[118:121], v[164:167], v[98:113]
	v_exp_f32_e32 v95, v95
	v_add_f32_e32 v245, v127, v245
	v_add_f32_e32 v246, v246, v94
	v_cvt_pk_bf16_f32 v206, v126, v127
	v_cvt_pk_bf16_f32 v209, v92, v93
	s_waitcnt lgkmcnt(1)
	v_mfma_f32_32x32x16_bf16 v[132:147], v[248:251], v[172:175], v[132:147]
	v_exp_f32_e32 v96, v96
	v_add_f32_e32 v245, v128, v245
	v_add_f32_e32 v246, v246, v95
	s_waitcnt lgkmcnt(0)
	v_mfma_f32_32x32x16_bf16 v[98:113], v[252:255], v[172:175], v[98:113]
	v_exp_f32_e32 v97, v97
	v_add_f32_e32 v245, v129, v245
	v_add_f32_e32 v246, v246, v96
	v_cvt_pk_bf16_f32 v207, v128, v129
	v_cvt_pk_bf16_f32 v210, v94, v95
	v_mov_b32_e32 v131, v97
	v_cvt_pk_bf16_f32 v211, v96, v97
	ds_read_b64_tr_b16 v[94:95], v0 offset:0
	ds_read_b64_tr_b16 v[96:97], v0 offset:2048
	ds_read_b64_tr_b16 v[90:91], v0 offset:4096
	ds_read_b64_tr_b16 v[92:93], v0 offset:6144
	ds_read_b64_tr_b16 v[86:87], v0 offset:8192
	ds_read_b64_tr_b16 v[88:89], v0 offset:10240
	ds_read_b64_tr_b16 v[82:83], v0 offset:12288
	ds_read_b64_tr_b16 v[84:85], v0 offset:14336
	v_cndmask_b32_e64 v114, 0, 1, s[0:1]
	v_cmp_ne_u32_e64 s[8:9], 1, v114
	s_andn2_b64 vcc, exec, s[0:1]
	s_cbranch_vccnz .Lh2_456
; template <bool FIRST, bool DOEXP = true>
; __device__ __forceinline__ void partialSM(f32x16& p0, f32x16& p1, float& m_reg, f32x16& negm, float& alpha, const bool track = true) {
;     ...
;   float pmax = p0[0];
; #pragma unroll
;   for (int r = 1; r < 16; ++r) pmax = fmaxf(pmax, p0[r]);
; #pragma unroll
;   for (int r = 0; r < 16; ++r) pmax = fmaxf(pmax, p1[r]);
;   { auto rr = __builtin_amdgcn_permlane32_swap(__float_as_uint(pmax), __float_as_uint(pmax), false, false);
;     pmax = fmaxf(__uint_as_float(rr[0]), __uint_as_float(rr[1])); }
;   if (!FIRST && __builtin_expect(__all(pmax <= THRL), 1)) { alpha = 1.f; }
;   else { const float dl = FIRST ? pmax : fmaxf(pmax, 0.f); m_reg += dl; alpha = FIRST ? 1.f : __builtin_amdgcn_exp2f(-dl);
; #pragma unroll
;     for (int r = 0; r < 16; ++r) { p0[r] -= dl; p1[r] -= dl; }
; #pragma unroll
;     for (int r = 0; r < 16; ++r) negm[r] = -m_reg;
;     asm volatile("" : "+v"(negm)); }
	v_max_f32_e32 v114, v133, v133
	v_max_f32_e32 v115, v132, v132
	v_max_f32_e32 v114, v115, v114
	v_max3_f32 v114, v114, v134, v135
	v_max3_f32 v114, v114, v136, v137
	v_max3_f32 v114, v114, v138, v139
	v_max3_f32 v114, v114, v140, v141
	v_max3_f32 v114, v114, v142, v143
	v_max3_f32 v114, v114, v144, v145
	v_max3_f32 v114, v114, v146, v147
	v_max3_f32 v114, v114, v98, v99
	v_max3_f32 v114, v114, v100, v101
	v_max3_f32 v114, v114, v102, v103
	v_max3_f32 v114, v114, v104, v105
	v_max3_f32 v114, v114, v106, v107
	v_max3_f32 v114, v114, v108, v109
	v_max3_f32 v114, v114, v110, v111
	v_max3_f32 v114, v114, v112, v113
	v_mov_b32_e32 v115, v114
	s_nop 1
	v_permlane32_swap_b32_e32 v114, v115
	v_max_f32_e32 v115, v115, v115
	v_max_f32_e32 v114, v114, v114
	v_max_f32_e32 v114, v114, v115
	v_cmp_ge_f32_e32 vcc, s69, v114
	s_cmp_eq_u64 vcc, exec
	v_mov_b32_e32 v130, 1.0
	s_cbranch_scc1 .Lh2_457
	v_max_f32_e32 v66, v114, v114
	v_max_f32_e32 v66, 0, v66
	v_exp_f32_e64 v130, -v66
	v_add_f32_e32 v222, v222, v66
	v_sub_f32_e32 v147, v147, v66
	v_sub_f32_e32 v146, v146, v66
	v_sub_f32_e32 v145, v145, v66
	v_sub_f32_e32 v144, v144, v66
	v_sub_f32_e32 v143, v143, v66
	v_sub_f32_e32 v142, v142, v66
	v_sub_f32_e32 v141, v141, v66
	v_sub_f32_e32 v140, v140, v66
	v_sub_f32_e32 v139, v139, v66
	v_sub_f32_e32 v138, v138, v66
	v_sub_f32_e32 v137, v137, v66
	v_sub_f32_e32 v136, v136, v66
	v_sub_f32_e32 v135, v135, v66
	v_sub_f32_e32 v134, v134, v66
	v_sub_f32_e32 v133, v133, v66
	v_sub_f32_e32 v132, v132, v66
	v_sub_f32_e32 v113, v113, v66
	v_sub_f32_e32 v112, v112, v66
	v_sub_f32_e32 v111, v111, v66
	v_sub_f32_e32 v110, v110, v66
	v_sub_f32_e32 v109, v109, v66
	v_sub_f32_e32 v108, v108, v66
	v_sub_f32_e32 v107, v107, v66
	v_sub_f32_e32 v106, v106, v66
	v_sub_f32_e32 v105, v105, v66
	v_sub_f32_e32 v104, v104, v66
	v_sub_f32_e32 v103, v103, v66
	v_sub_f32_e32 v102, v102, v66
	v_sub_f32_e32 v101, v101, v66
	v_sub_f32_e32 v100, v100, v66
	v_sub_f32_e32 v99, v99, v66
	v_sub_f32_e32 v98, v98, v66
	v_xor_b32_e32 v66, 0x80000000, v222
	v_mov_b32_e32 v67, v66
	v_mov_b32_e32 v68, v66
	v_mov_b32_e32 v69, v66
	v_mov_b32_e32 v70, v66
	v_mov_b32_e32 v71, v66
	v_mov_b32_e32 v72, v66
	v_mov_b32_e32 v73, v66
	v_mov_b32_e32 v74, v66
	v_mov_b32_e32 v75, v66
	v_mov_b32_e32 v76, v66
	v_mov_b32_e32 v77, v66
	v_mov_b32_e32 v78, v66
	v_mov_b32_e32 v79, v66
	v_mov_b32_e32 v80, v66
	v_mov_b32_e32 v81, v66
	s_branch .Lh2_457

; #define SBAR() __builtin_amdgcn_sched_barrier(0)
; __device__ __forceinline__ unsigned cvtpk(float lo, float hi) { unsigned r; asm volatile("v_cvt_pk_bf16_f32 %0, %1, %2" : "=v"(r) : "v"(lo), "v"(hi)); return r; }
; template <bool FIRST, bool DOEXP = true>
; __device__ __forceinline__ void partialSM(f32x16& p0, f32x16& p1, float& m_reg, f32x16& negm, float& alpha, const bool track = true) {
;     ...
;   float pmax = p0[0];
; #pragma unroll
;   for (int r = 1; r < 16; ++r) pmax = fmaxf(pmax, p0[r]);
; #pragma unroll
;   for (int r = 0; r < 16; ++r) pmax = fmaxf(pmax, p1[r]);
;   { auto rr = __builtin_amdgcn_permlane32_swap(__float_as_uint(pmax), __float_as_uint(pmax), false, false);
;     pmax = fmaxf(__uint_as_float(rr[0]), __uint_as_float(rr[1])); }
;   if (!FIRST && __builtin_expect(__all(pmax <= THRL), 1)) { alpha = 1.f; }
; __device__ __forceinline__ void qkt_fin(f32x16& n0, f32x16& n1, const bf16_t* Ks, const bf16x8* qr, const f32x16& negm, int r32, int hi, ...
;   float psa = 0.f, psb = 0.f; u32x4 wa, wb, wc, wd;
;     ...
; #pragma unroll
;   for (int d0 = 0; d0 < 8; ++d0) { int cb = (d0 * 16 + hi * 8) * 2;
;     bf16x8 b0 = *reinterpret_cast<const bf16x8*>((const char*)Ks + KSWZ(r32, cb));
;     bf16x8 b1 = *reinterpret_cast<const bf16x8*>((const char*)Ks + KSWZ(32 + r32, cb));
;     SBAR(); if (d0 == 0) n0 = __builtin_amdgcn_mfma_f32_32x32x16_bf16(b0, qr[0], negm, 0, 0, 0); else n0 = __builtin_amdgcn_mfma_f32_32x32x16_bf16(b0, qr[d0], n0, 0, 0, 0);
;     SBAR(); QF_CHUNK(2 * d0); SBAR();
;     if (d0 == 0) n1 = __builtin_amdgcn_mfma_f32_32x32x16_bf16(b1, qr[0], negm, 0, 0, 0); else n1 = __builtin_amdgcn_mfma_f32_32x32x16_bf16(b1, qr[d0], n1, 0, 0, 0);
;     SBAR(); QF_CHUNK(2 * d0 + 1); SBAR();
;     if (d0 == 7) { vf8_read<0>(vf0, vbv); SBAR(); } }
;     ...
;   psb += P1[15]; wd[3] = cvtpk(P1[14], P1[15]);
;   l_reg = l_reg * alpha + (psa + psb);
;   pa0 = *reinterpret_cast<bf16x8*>(&wa); pa1 = *reinterpret_cast<bf16x8*>(&wb); pa2 = *reinterpret_cast<bf16x8*>(&wc); pa3 = *reinterpret_cast<bf16x8*>(&wd);
; }
.Lh2_461:
	s_waitcnt lgkmcnt(0)
	s_waitcnt vmcnt(0)
	s_barrier
	v_add_u32_e32 v208, s99, v236
	ds_read_b128 v[204:207], v208 offset:16384
	ds_read_b128 v[208:211], v208 offset:24576
	v_add_u32_e32 v252, s99, v237
	ds_read_b128 v[248:251], v252 offset:16384
	ds_read_b128 v[252:255], v252 offset:24576
	v_add_u32_e32 v203, s96, v235
	s_waitcnt lgkmcnt(3)
	v_mfma_f32_32x32x16_bf16 v[114:129], v[204:207], v[152:155], v[66:81]
	v_exp_f32_e32 v98, v98
	s_waitcnt lgkmcnt(2)
	v_mfma_f32_32x32x16_bf16 v[82:97], v[208:211], v[152:155], v[66:81]
	v_exp_f32_e32 v99, v99
	v_add_f32_e32 v201, v133, v132
	v_cvt_pk_bf16_f32 v132, v132, v133
	v_add_u32_e32 v208, s99, v238
	ds_read_b128 v[204:207], v208 offset:16384
	ds_read_b128 v[208:211], v208 offset:24576
	s_add_i32 s79, s98, s100
	s_add_i32 m0, s79, 0x4000
	s_add_i32 s79, s79, 0x6000
	global_load_lds_dwordx4 v[180:181], off
	s_waitcnt lgkmcnt(3)
	v_mfma_f32_32x32x16_bf16 v[114:129], v[248:251], v[160:163], v[114:129]
	v_exp_f32_e32 v100, v100
	v_add_f32_e32 v201, v134, v201
	v_add_f32_e32 v202, v98, v99
	s_waitcnt lgkmcnt(2)
	v_mfma_f32_32x32x16_bf16 v[82:97], v[252:255], v[160:163], v[82:97]
	v_exp_f32_e32 v101, v101
	v_add_f32_e32 v201, v135, v201
	v_add_f32_e32 v202, v202, v100
	v_cvt_pk_bf16_f32 v133, v134, v135
	v_cvt_pk_bf16_f32 v196, v98, v99
	v_add_u32_e32 v252, s99, v239
	ds_read_b128 v[248:251], v252 offset:16384
	ds_read_b128 v[252:255], v252 offset:24576
	s_mov_b32 m0, s79
	s_add_i32 s79, s98, s101
	global_load_lds_dwordx4 v[182:183], off
	s_waitcnt lgkmcnt(3)
	v_mfma_f32_32x32x16_bf16 v[114:129], v[204:207], v[148:151], v[114:129]
	v_exp_f32_e32 v102, v102
	v_add_f32_e32 v201, v136, v201
	v_add_f32_e32 v202, v202, v101
	s_waitcnt lgkmcnt(2)
	v_mfma_f32_32x32x16_bf16 v[82:97], v[208:211], v[148:151], v[82:97]
	v_exp_f32_e32 v103, v103
	v_add_f32_e32 v201, v137, v201
	v_add_f32_e32 v202, v202, v102
	v_cvt_pk_bf16_f32 v134, v136, v137
	v_cvt_pk_bf16_f32 v197, v100, v101
	v_add_u32_e32 v208, s99, v240
	ds_read_b128 v[204:207], v208 offset:16384
	ds_read_b128 v[208:211], v208 offset:24576
	s_mov_b32 m0, s79
	s_add_i32 s79, s79, 0x380
	global_load_lds_dwordx4 v[214:215], off
	s_waitcnt lgkmcnt(3)
	v_mfma_f32_32x32x16_bf16 v[114:129], v[248:251], v[156:159], v[114:129]
	v_exp_f32_e32 v104, v104
	v_add_f32_e32 v201, v138, v201
	v_add_f32_e32 v202, v202, v103
	s_waitcnt lgkmcnt(2)
	v_mfma_f32_32x32x16_bf16 v[82:97], v[252:255], v[156:159], v[82:97]
	v_exp_f32_e32 v105, v105
	v_add_f32_e32 v201, v139, v201
	v_add_f32_e32 v202, v202, v104
	v_cvt_pk_bf16_f32 v135, v138, v139
	v_cvt_pk_bf16_f32 v198, v102, v103
	v_add_u32_e32 v252, s99, v241
	ds_read_b128 v[248:251], v252 offset:16384
	ds_read_b128 v[252:255], v252 offset:24576
	s_mov_b32 m0, s79
	s_nop 0
	global_load_lds_dwordx4 v[214:215], off offset:128
	v_lshl_add_u64 v[180:181], v[180:181], 0, s[76:77]
	v_lshl_add_u64 v[182:183], v[182:183], 0, s[76:77]
	v_lshl_add_u64 v[214:215], v[214:215], 0, s[76:77]
	s_waitcnt lgkmcnt(3)
	v_mfma_f32_32x32x16_bf16 v[114:129], v[204:207], v[168:171], v[114:129]
	v_exp_f32_e32 v106, v106
	v_add_f32_e32 v201, v140, v201
	v_add_f32_e32 v202, v202, v105
	s_waitcnt lgkmcnt(2)
	v_mfma_f32_32x32x16_bf16 v[82:97], v[208:211], v[168:171], v[82:97]
	v_exp_f32_e32 v107, v107
	v_add_f32_e32 v201, v141, v201
	v_add_f32_e32 v202, v202, v106
	v_cvt_pk_bf16_f32 v136, v140, v141
	v_cvt_pk_bf16_f32 v199, v104, v105
	v_add_u32_e32 v208, s99, v242
	ds_read_b128 v[204:207], v208 offset:16384
	ds_read_b128 v[208:211], v208 offset:24576
	s_waitcnt lgkmcnt(3)
	v_mfma_f32_32x32x16_bf16 v[114:129], v[248:251], v[176:179], v[114:129]
	v_exp_f32_e32 v108, v108
	v_add_f32_e32 v201, v142, v201
	v_add_f32_e32 v202, v202, v107
	s_waitcnt lgkmcnt(2)
	v_mfma_f32_32x32x16_bf16 v[82:97], v[252:255], v[176:179], v[82:97]
	v_exp_f32_e32 v109, v109
	v_add_f32_e32 v201, v143, v201
	v_add_f32_e32 v202, v202, v108
	v_cvt_pk_bf16_f32 v137, v142, v143
	v_cvt_pk_bf16_f32 v140, v106, v107
	v_add_u32_e32 v252, s99, v243
	ds_read_b128 v[248:251], v252 offset:16384
	ds_read_b128 v[252:255], v252 offset:24576
	s_waitcnt lgkmcnt(3)
	v_mfma_f32_32x32x16_bf16 v[114:129], v[204:207], v[164:167], v[114:129]
	v_exp_f32_e32 v110, v110
	v_add_f32_e32 v201, v144, v201
	v_add_f32_e32 v202, v202, v109
	s_waitcnt lgkmcnt(2)
	v_mfma_f32_32x32x16_bf16 v[82:97], v[208:211], v[164:167], v[82:97]
	v_exp_f32_e32 v111, v111
	v_add_f32_e32 v201, v145, v201
	v_add_f32_e32 v202, v202, v110
	v_cvt_pk_bf16_f32 v138, v144, v145
	v_cvt_pk_bf16_f32 v141, v108, v109
	s_waitcnt lgkmcnt(1)
	v_mfma_f32_32x32x16_bf16 v[114:129], v[248:251], v[172:175], v[114:129]
	v_exp_f32_e32 v112, v112
	v_add_f32_e32 v201, v146, v201
	v_add_f32_e32 v202, v202, v111
	s_waitcnt lgkmcnt(0)
	v_mfma_f32_32x32x16_bf16 v[82:97], v[252:255], v[172:175], v[82:97]
	v_exp_f32_e32 v113, v113
	v_add_f32_e32 v201, v147, v201
	v_add_f32_e32 v202, v202, v112
	v_cvt_pk_bf16_f32 v139, v146, v147
	v_cvt_pk_bf16_f32 v142, v110, v111
	ds_read_b64_tr_b16 v[144:145], v203 offset:0
	ds_read_b64_tr_b16 v[146:147], v203 offset:2048
	s_nop 0
	ds_read_b64_tr_b16 v[106:107], v203 offset:4096
	ds_read_b64_tr_b16 v[108:109], v203 offset:6144
	ds_read_b64_tr_b16 v[102:103], v203 offset:8192
	ds_read_b64_tr_b16 v[104:105], v203 offset:10240
	ds_read_b64_tr_b16 v[98:99], v203 offset:12288
	ds_read_b64_tr_b16 v[100:101], v203 offset:14336
	v_cvt_pk_bf16_f32 v143, v112, v113
	s_and_b64 vcc, exec, s[8:9]
	v_mov_b32_e32 v200, 1.0
	s_cbranch_vccnz .Lh2_463
	v_max_f32_e32 v110, v115, v115
	v_max_f32_e32 v111, v114, v114
	v_max_f32_e32 v110, v111, v110
	v_max3_f32 v110, v110, v116, v117
	v_max3_f32 v110, v110, v118, v119
	v_max3_f32 v110, v110, v120, v121
	v_max3_f32 v110, v110, v122, v123
	v_max3_f32 v110, v110, v124, v125
	v_max3_f32 v110, v110, v126, v127
	v_max3_f32 v110, v110, v128, v129
	v_max3_f32 v110, v110, v82, v83
	v_max3_f32 v110, v110, v84, v85
	v_max3_f32 v110, v110, v86, v87
	v_max3_f32 v110, v110, v88, v89
	v_max3_f32 v110, v110, v90, v91
	v_max3_f32 v110, v110, v92, v93
	v_max3_f32 v110, v110, v94, v95
	v_max3_f32 v110, v110, v96, v97
	v_mov_b32_e32 v111, v110
	s_nop 1
	v_permlane32_swap_b32_e32 v110, v111
	v_max_f32_e32 v111, v111, v111
	v_max_f32_e32 v110, v110, v110
	v_max_f32_e32 v110, v110, v111
	v_cmp_ge_f32_e32 vcc, s69, v110
	s_cmp_eq_u64 vcc, exec
	v_mov_b32_e32 v200, 1.0
	s_cbranch_scc0 .Lh2_469
